# mLSTM preamble: all 16 gate loads prefetched before the scan loop (register queue)
# speedup vs baseline: 1.0145x; 1.0053x over previous
; __device__ __forceinline__ void mlstm_item(const Args& a, LAS unsigned char* L, bool sample, int b, int hh, int sl, bool dry = false) {
;     ...
;     for (int c = wave; c < nchunks; c += 8) {
;         const size_t r0 = (size_t)(rowbase + c * 32 + t32);
;         const float ig = gates[r0 * 8 + hh] + bi, xg = gates[r0 * 8 + 4 + hh] + bfv;
.LBB0_647:
	s_or_b64 exec, exec, s[4:5]
	s_lshl_b32 s4, s91, 9
	v_and_b32_e32 v27, 63, v83
	s_and_b32 s42, s4, 0x7000
	s_ashr_i32 s55, s12, 6
	s_cmp_gt_i32 s55, 63
	v_cmp_eq_u32_e32 vcc, 31, v27
	s_cbranch_scc1 .LBB0_654
	s_add_u32 s10, s74, s93
	s_addc_u32 s11, s75, 0
	s_lshl_b32 s8, s58, 9
	s_add_i32 s8, s42, s8
	v_and_b32_e32 v20, 16, v83
	s_and_b32 s8, s8, 0xfffff800
	s_lshl_b32 s9, s55, 5
	v_cmp_eq_u32_e64 s[4:5], 0, v20
	v_lshlrev_b32_e32 v20, 2, v27
	s_add_i32 s8, s8, s9
	v_cmp_gt_u32_e64 s[6:7], 32, v27
	s_add_i32 s14, s55, -8
	s_lshl_b32 s15, s55, 2
	v_lshl_add_u32 v30, s55, 7, v20
	v_or_b32_e32 v20, s8, v24
	s_mov_b64 s[8:9], 0x2000
	v_ashrrev_i32_e32 v21, 31, v20
	v_lshlrev_b64 v[32:33], 5, v[20:21]
	v_lshl_add_u64 v[32:33], s[10:11], 0, v[32:33]
	global_load_dword v191, v[32:33], off offset:16
	global_load_dword v190, v[32:33], off
	v_lshl_add_u64 v[32:33], v[32:33], 0, s[8:9]
	global_load_dword v193, v[32:33], off offset:16
	global_load_dword v192, v[32:33], off
	v_lshl_add_u64 v[32:33], v[32:33], 0, s[8:9]
	global_load_dword v195, v[32:33], off offset:16
	global_load_dword v194, v[32:33], off
	v_lshl_add_u64 v[32:33], v[32:33], 0, s[8:9]
	global_load_dword v197, v[32:33], off offset:16
	global_load_dword v196, v[32:33], off
	v_lshl_add_u64 v[32:33], v[32:33], 0, s[8:9]
	global_load_dword v199, v[32:33], off offset:16
	global_load_dword v198, v[32:33], off
	v_lshl_add_u64 v[32:33], v[32:33], 0, s[8:9]
	global_load_dword v201, v[32:33], off offset:16
	global_load_dword v200, v[32:33], off
	v_lshl_add_u64 v[32:33], v[32:33], 0, s[8:9]
	global_load_dword v203, v[32:33], off offset:16
	global_load_dword v202, v[32:33], off
	v_lshl_add_u64 v[32:33], v[32:33], 0, s[8:9]
	global_load_dword v205, v[32:33], off offset:16
	global_load_dword v204, v[32:33], off
	s_branch .LBB0_650
.LBB0_649:
	s_or_b64 exec, exec, s[8:9]
	v_mov_b32_e32 v190, v192
	v_mov_b32_e32 v191, v193
	v_mov_b32_e32 v192, v194
	v_mov_b32_e32 v193, v195
	v_mov_b32_e32 v194, v196
	v_mov_b32_e32 v195, v197
	v_mov_b32_e32 v196, v198
	v_mov_b32_e32 v197, v199
	v_mov_b32_e32 v198, v200
	v_mov_b32_e32 v199, v201
	v_mov_b32_e32 v200, v202
	v_mov_b32_e32 v201, v203
	v_mov_b32_e32 v202, v204
	v_mov_b32_e32 v203, v205
	s_add_i32 s14, s14, 8
	s_add_i32 s15, s15, 32
	v_add_u32_e32 v30, 0x400, v30
	s_cmp_gt_i32 s14, 55
	v_add_u32_e32 v20, 0x100, v20
	s_cbranch_scc1 .LBB0_654
; __device__ __forceinline__ void mlstm_item(const Args& a, LAS unsigned char* L, bool sample, int b, int hh, int sl, bool dry = false) {
;     ...
;         const size_t r0 = (size_t)(rowbase + c * 32 + t32);
;         const float ig = gates[r0 * 8 + hh] + bi, xg = gates[r0 * 8 + 4 + hh] + bfv;
;         const float lf = fminf(xg, 0.f) - log1pf(__expf(-fabsf(xg)));
;         float F = lf;
;         F += dpp_shr_f(0.f, F, 1); F += dpp_shr_f(0.f, F, 2); F += dpp_shr_f(0.f, F, 4); F += dpp_shr_f(0.f, F, 8);
;         { const float r15 = __int_as_float(__builtin_amdgcn_readlane(__float_as_int(F), 15)); if (lane & 16) F += r15; }
;         const float aa = ig - F;
;         const float NINF = -__builtin_inff();
;         float cm = aa;
;         cm = fmaxf(cm, dpp_shr_f(NINF, cm, 1)); cm = fmaxf(cm, dpp_shr_f(NINF, cm, 2)); cm = fmaxf(cm, dpp_shr_f(NINF, cm, 4)); cm = fmaxf(cm, dpp_shr_f(NINF, cm, 8));
;         { const float r15 = __int_as_float(__builtin_amdgcn_readlane(__float_as_int(cm), 15)); if (lane & 16) cm = fmaxf(cm, r15); }
;         if (lane < 32) { GAA[c * 32 + lane] = aa; GFM[c * 32 + lane] = cm; GEN[c * 32 + lane] = F; }
;         if (lane == 31) { GDL[c] = F; GM0[c] = cm; }
.LBB0_650:
	s_waitcnt vmcnt(0)
	v_mov_b32_e32 v21, v191
	v_mov_b32_e32 v31, v190
	s_mov_b32 s8, 0xbfb8aa3b
	s_mov_b32 s9, 0x3f2aaaab
	s_mov_b32 s16, 0x3f317218
	s_mov_b32 s17, 0x7f800000
	s_mov_b32 s56, 0x33800000
	v_mov_b32_e32 v34, 0xff800000
	v_mov_b32_e32 v35, 0xff800000
	v_mov_b32_e32 v36, 0xff800000
	v_add_f32_e32 v21, v29, v21
	v_mul_f32_e64 v32, |v21|, s8
	v_exp_f32_e32 v37, v32
	v_min_f32_e32 v21, 0, v21
	v_add_f32_e32 v31, v28, v31
	v_add_f32_e32 v38, 1.0, v37
	v_add_f32_e32 v39, -1.0, v38
	v_frexp_mant_f32_e32 v40, v38
	v_cvt_f64_f32_e32 v[32:33], v38
	v_sub_f32_e32 v41, v39, v38
	v_frexp_exp_i32_f64_e32 v32, v[32:33]
	v_cmp_gt_f32_e64 s[8:9], s9, v40
	v_sub_f32_e32 v39, v37, v39
	v_add_f32_e32 v33, 1.0, v41
	v_subbrev_co_u32_e64 v32, s[8:9], 0, v32, s[8:9]
	v_add_f32_e32 v33, v39, v33
	v_sub_u32_e32 v39, 0, v32
	v_cvt_f32_i32_e32 v32, v32
	v_ldexp_f32 v38, v38, v39
	v_ldexp_f32 v33, v33, v39
	v_add_f32_e32 v39, -1.0, v38
	v_add_f32_e32 v40, 1.0, v38
	v_add_f32_e32 v41, 1.0, v39
	v_add_f32_e32 v42, -1.0, v40
	v_sub_f32_e32 v41, v38, v41
	v_sub_f32_e32 v38, v38, v42
	v_mul_f32_e32 v42, 0x3f317218, v32
	v_add_f32_e32 v41, v33, v41
	v_add_f32_e32 v33, v33, v38
	v_fma_f32 v38, v32, s16, -v42
	v_add_f32_e32 v43, v39, v41
	v_add_f32_e32 v44, v40, v33
	v_fmac_f32_e32 v38, 0xb102e308, v32
	v_sub_f32_e32 v32, v43, v39
	v_sub_f32_e32 v39, v44, v40
	v_rcp_f32_e32 v40, v44
	v_add_f32_e32 v45, v42, v38
	v_sub_f32_e32 v33, v33, v39
	v_sub_f32_e32 v39, v45, v42
	v_sub_f32_e32 v38, v38, v39
	v_mul_f32_e32 v39, v43, v40
	v_sub_f32_e32 v32, v41, v32
	v_mul_f32_e32 v41, v44, v39
	v_fma_f32 v42, v39, v44, -v41
	v_fmac_f32_e32 v42, v39, v33
	v_add_f32_e32 v46, v41, v42
	v_sub_f32_e32 v47, v43, v46
	v_sub_f32_e32 v41, v46, v41
	v_sub_f32_e32 v43, v43, v47
	v_sub_f32_e32 v41, v41, v42
	v_sub_f32_e32 v42, v43, v46
	v_add_f32_e32 v32, v32, v42
	v_add_f32_e32 v32, v41, v32
	v_add_f32_e32 v41, v47, v32
	v_mul_f32_e32 v42, v40, v41
	v_sub_f32_e32 v43, v47, v41
	v_mul_f32_e32 v46, v44, v42
	v_add_f32_e32 v32, v32, v43
	v_add_f32_e32 v43, v39, v42
	v_fma_f32 v44, v42, v44, -v46
	v_sub_f32_e32 v39, v43, v39
	v_fmac_f32_e32 v44, v42, v33
	v_sub_f32_e32 v33, v42, v39
	v_add_f32_e32 v39, v46, v44
	v_sub_f32_e32 v42, v39, v46
	v_sub_f32_e32 v46, v41, v39
	v_sub_f32_e32 v41, v41, v46
	v_sub_f32_e32 v39, v41, v39
	v_sub_f32_e32 v42, v42, v44
	v_add_f32_e32 v32, v32, v39
	v_add_f32_e32 v32, v42, v32
	v_add_f32_e32 v32, v46, v32
	v_mul_f32_e32 v32, v40, v32
	v_add_f32_e32 v32, v33, v32
	v_add_f32_e32 v33, v43, v32
	v_mul_f32_e32 v39, v33, v33
	v_fmamk_f32 v42, v39, 0x3e9b6dac, v78
	v_sub_f32_e32 v40, v33, v43
	v_ldexp_f32 v41, v33, 1
	v_mul_f32_e32 v33, v33, v39
	v_fmaak_f32 v39, v39, v42, 0x3f2aaada
	v_mul_f32_e32 v33, v33, v39
	v_add_f32_e32 v39, v41, v33
	v_sub_f32_e32 v32, v32, v40
	v_sub_f32_e32 v40, v39, v41
	v_ldexp_f32 v32, v32, 1
	v_sub_f32_e32 v33, v33, v40
	v_add_f32_e32 v32, v32, v33
	v_add_f32_e32 v33, v39, v32
	v_sub_f32_e32 v39, v33, v39
	v_add_f32_e32 v40, v45, v33
	v_sub_f32_e32 v32, v32, v39
	v_sub_f32_e32 v39, v40, v45
	v_sub_f32_e32 v41, v40, v39
	v_sub_f32_e32 v33, v33, v39
	v_add_f32_e32 v39, v38, v32
	v_sub_f32_e32 v41, v45, v41
	v_sub_f32_e32 v42, v39, v38
	v_add_f32_e32 v33, v33, v41
	v_sub_f32_e32 v41, v39, v42
	v_sub_f32_e32 v32, v32, v42
	v_sub_f32_e32 v38, v38, v41
	v_add_f32_e32 v33, v39, v33
	v_add_f32_e32 v32, v32, v38
	v_add_f32_e32 v38, v40, v33
	v_sub_f32_e32 v39, v38, v40
	v_sub_f32_e32 v33, v33, v39
	v_add_f32_e32 v32, v32, v33
	v_add_f32_e32 v32, v38, v32
	v_cmp_neq_f32_e64 s[8:9], s17, v37
	s_nop 1
	v_cndmask_b32_e64 v32, v80, v32, s[8:9]
	v_cmp_ngt_f32_e64 s[8:9], -1.0, v37
	s_nop 1
	v_cndmask_b32_e64 v32, v81, v32, s[8:9]
	v_cmp_neq_f32_e64 s[8:9], -1.0, v37
	s_nop 1
	v_cndmask_b32_e64 v32, v79, v32, s[8:9]
	v_cmp_lt_f32_e64 s[8:9], |v37|, s56
	s_nop 1
	v_cndmask_b32_e64 v32, v32, v37, s[8:9]
	v_sub_f32_e32 v21, v21, v32
	s_nop 1
	v_add_f32_dpp v21, v21, v21 row_shr:1 row_mask:0xf bank_mask:0xf bound_ctrl:1
	s_nop 1
	v_add_f32_dpp v21, v21, v21 row_shr:2 row_mask:0xf bank_mask:0xf bound_ctrl:1
	s_nop 1
	v_add_f32_dpp v21, v21, v21 row_shr:4 row_mask:0xf bank_mask:0xf bound_ctrl:1
	s_nop 1
	v_add_f32_dpp v21, v21, v21 row_shr:8 row_mask:0xf bank_mask:0xf bound_ctrl:1
	s_nop 0
	v_readlane_b32 s8, v21, 15
	s_nop 1
	v_add_f32_e32 v32, s8, v21
	v_cndmask_b32_e64 v21, v32, v21, s[4:5]
	v_sub_f32_e32 v31, v31, v21
	s_nop 1
	v_mov_b32_dpp v34, v31 row_shr:1 row_mask:0xf bank_mask:0xf
	v_max_f32_e32 v32, v34, v34
	v_max_f32_e32 v32, v31, v32
	s_nop 1
	v_mov_b32_dpp v35, v32 row_shr:2 row_mask:0xf bank_mask:0xf
	v_max_f32_e32 v33, v35, v35
	v_max_f32_e32 v32, v32, v33
	s_nop 1
	v_mov_b32_dpp v36, v32 row_shr:4 row_mask:0xf bank_mask:0xf
	v_max_f32_e32 v33, v36, v36
	v_max_f32_e32 v32, v32, v33
	v_mov_b32_e32 v33, 0xff800000
	s_nop 1
	v_mov_b32_dpp v33, v32 row_shr:8 row_mask:0xf bank_mask:0xf
	v_max_f32_e32 v33, v33, v33
	v_max_f32_e32 v32, v32, v33
	s_nop 0
	v_readlane_b32 s8, v32, 15
	s_nop 1
	v_max_f32_e64 v33, s8, s8
	v_max_f32_e32 v33, v32, v33
	v_cndmask_b32_e64 v32, v33, v32, s[4:5]
	s_and_saveexec_b64 s[8:9], s[6:7]
	s_cbranch_execz .LBB0_652
	v_add_u32_e32 v33, 0, v30
	v_add_u32_e32 v34, 0x18500, v33
	v_add_u32_e32 v35, 0x16500, v33
	v_add_u32_e32 v33, 0x1a500, v33
	ds_write_b32 v34, v31
	ds_write_b32 v35, v32
	ds_write_b32 v33, v21
